# attention epilogue: the 16 subln gain loads hoisted to the epilogue top (were load, vmcnt(0), store x16 serialized)
# speedup vs baseline: 1.0060x; 1.0060x over previous
; __device__ __forceinline__ void attn_unit(LAS unsigned char* lds, const bf16_t* Qb, const bf16_t* Kb, const bf16_t* Vb, bf16_t* mix,
;                                           int b, int head, int qbase  , float lam, float post_scale, const float* subg) {
;     ...
;     if (c == 0) {
;         const float i0 = 1.f / lt;
;         float ss = 0.f;
; #pragma unroll
;         for (int d = 0; d < 4; ++d)
; #pragma unroll
;             for (int i = 0; i < 16; ++i) { const float o = O[d][i] * i0 - X[(d * 16 + i) * 64]; O[d][i] = o; ss += o * o; }
;         ss += __shfl_xor(ss, 32);
;         const float rn = rsqrtf(ss * (1.f / 128.f) + EPSN) * post_scale;
;         const int qrow = qbase < CTXL ? (MLAT + b * CTXL + qidx_e) : (b * SEQ + qidx_e - CTXL);
;         bf16_t* orow = mix + (size_t)qrow * DM + head * 128;
; #pragma unroll
;         for (int d = 0; d < 4; ++d)
; #pragma unroll
;             for (int i4 = 0; i4 < 4; ++i4) {
;                 const int dv = 32 * d + 8 * i4 + 4 * h_e;
;                 const f32x4 g = *(const f32x4*)(subg + dv);
.LBB0_377:
	s_waitcnt lgkmcnt(0)
	s_barrier
	s_cmpk_gt_u32 s43, 0xff
	s_cbranch_scc1 .LBB0_337
	v_lshrrev_b32_e32 v83, 3, v222
	v_and_b32_e32 v83, 4, v83
	v_lshlrev_b32_e32 v83, 2, v83
	global_load_dwordx4 v[84:87], v83, s[10:11]
	global_load_dwordx4 v[88:91], v83, s[10:11] offset:32
	global_load_dwordx4 v[92:95], v83, s[10:11] offset:64
	global_load_dwordx4 v[96:99], v83, s[10:11] offset:96
	global_load_dwordx4 v[100:103], v83, s[10:11] offset:128
	global_load_dwordx4 v[104:107], v83, s[10:11] offset:160
	global_load_dwordx4 v[108:111], v83, s[10:11] offset:192
	global_load_dwordx4 v[112:115], v83, s[10:11] offset:224
	global_load_dwordx4 v[116:119], v83, s[10:11] offset:256
	global_load_dwordx4 v[120:123], v83, s[10:11] offset:288
	global_load_dwordx4 v[124:127], v83, s[10:11] offset:320
	global_load_dwordx4 v[128:131], v83, s[10:11] offset:352
	global_load_dwordx4 v[132:135], v83, s[10:11] offset:384
	global_load_dwordx4 v[136:139], v83, s[10:11] offset:416
	global_load_dwordx4 v[140:143], v83, s[10:11] offset:448
	global_load_dwordx4 v[144:147], v83, s[10:11] offset:480
	v_div_scale_f32 v65, s[14:15], v64, v64, 1.0
	v_rcp_f32_e32 v66, v65
	s_bfe_u32 s0, s41, 0x10002
	s_and_b64 s[12:13], s[12:13], exec
	s_cselect_b32 s1, 13, 8
	v_fma_f32 v68, -v65, v66, 1.0
	v_fmac_f32_e32 v66, v68, v66
	v_div_scale_f32 v68, vcc, 1.0, v64, 1.0
	v_mul_f32_e32 v69, v68, v66
	v_fma_f32 v70, -v65, v69, v68
	v_fmac_f32_e32 v69, v70, v66
	v_fma_f32 v65, -v65, v69, v68
	v_div_fmas_f32 v65, v65, v66, v69
	ds_read2st64_b32 v[68:69], v79 offset1:1
	ds_read2st64_b32 v[70:71], v79 offset0:20 offset1:21
	v_div_fixup_f32 v64, v65, v64, 1.0
	s_movk_i32 s12, 0xff00
	s_cselect_b32 s12, s12, 0x4000
	s_waitcnt lgkmcnt(1)
	v_fma_f32 v65, v48, v64, -v68
	v_fma_f32 v48, v49, v64, -v69
	ds_read2st64_b32 v[68:69], v79 offset0:2 offset1:3
	v_mul_f32_e32 v80, v48, v48
	v_fmac_f32_e32 v80, v65, v65
	s_lshl_b32 s0, s0, s1
	s_add_i32 s0, s0, s12
	s_waitcnt lgkmcnt(0)
	v_fma_f32 v49, v50, v64, -v68
	v_fma_f32 v50, v51, v64, -v69
	ds_read2st64_b32 v[68:69], v79 offset0:4 offset1:5
	v_fmac_f32_e32 v80, v49, v49
	v_fmac_f32_e32 v80, v50, v50
	s_add_i32 s0, s0, s42
	s_waitcnt lgkmcnt(0)
	v_fma_f32 v51, v52, v64, -v68
	v_fma_f32 v52, v53, v64, -v69
	ds_read2st64_b32 v[68:69], v79 offset0:6 offset1:7
	v_fmac_f32_e32 v80, v51, v51
	v_fmac_f32_e32 v80, v52, v52
	s_waitcnt lgkmcnt(0)
	v_fma_f32 v53, v54, v64, -v68
	v_fma_f32 v54, v55, v64, -v69
	ds_read2st64_b32 v[68:69], v79 offset0:8 offset1:9
	v_fmac_f32_e32 v80, v53, v53
	v_fmac_f32_e32 v80, v54, v54
	s_waitcnt lgkmcnt(0)
	v_fma_f32 v56, v56, v64, -v68
	v_fma_f32 v55, v57, v64, -v69
	ds_read2st64_b32 v[68:69], v79 offset0:10 offset1:11
	v_fmac_f32_e32 v80, v56, v56
	v_fmac_f32_e32 v80, v55, v55
	s_waitcnt lgkmcnt(0)
	v_fma_f32 v66, v58, v64, -v68
	v_fma_f32 v58, v59, v64, -v69
	ds_read2st64_b32 v[68:69], v79 offset0:12 offset1:13
	v_fmac_f32_e32 v80, v66, v66
	v_fmac_f32_e32 v80, v58, v58
	s_waitcnt lgkmcnt(0)
	v_fma_f32 v59, v60, v64, -v68
	v_fma_f32 v57, v61, v64, -v69
	ds_read2st64_b32 v[60:61], v79 offset0:14 offset1:15
	v_fmac_f32_e32 v80, v59, v59
	v_fmac_f32_e32 v80, v57, v57
	s_waitcnt lgkmcnt(0)
	v_fma_f32 v68, v62, v64, -v60
	v_fma_f32 v61, v63, v64, -v61
	ds_read2st64_b32 v[62:63], v79 offset0:16 offset1:17
	v_fmac_f32_e32 v80, v68, v68
	v_fmac_f32_e32 v80, v61, v61
	s_waitcnt lgkmcnt(0)
	v_fma_f32 v60, v32, v64, -v62
	v_fma_f32 v32, v33, v64, -v63
	ds_read2st64_b32 v[62:63], v79 offset0:18 offset1:19
	v_fma_f32 v33, v37, v64, -v71
	v_fmac_f32_e32 v80, v60, v60
	v_fmac_f32_e32 v80, v32, v32
	s_waitcnt lgkmcnt(0)
	v_fma_f32 v62, v34, v64, -v62
	v_fma_f32 v34, v35, v64, -v63
	v_fma_f32 v35, v36, v64, -v70
	ds_read2st64_b32 v[36:37], v79 offset0:22 offset1:23
	v_fmac_f32_e32 v80, v62, v62
	v_fmac_f32_e32 v80, v34, v34
	v_fmac_f32_e32 v80, v35, v35
	v_fmac_f32_e32 v80, v33, v33
	s_waitcnt lgkmcnt(0)
	v_fma_f32 v69, v38, v64, -v36
	v_fma_f32 v63, v39, v64, -v37
	ds_read2st64_b32 v[38:39], v79 offset0:24 offset1:25
	v_fmac_f32_e32 v80, v69, v69
	v_fmac_f32_e32 v80, v63, v63
	s_waitcnt lgkmcnt(0)
	v_fma_f32 v37, v40, v64, -v38
	v_fma_f32 v36, v41, v64, -v39
	ds_read2st64_b32 v[38:39], v79 offset0:26 offset1:27
	v_fmac_f32_e32 v80, v37, v37
	v_fmac_f32_e32 v80, v36, v36
	s_waitcnt lgkmcnt(0)
	v_fma_f32 v41, v42, v64, -v38
	v_fma_f32 v39, v43, v64, -v39
	ds_read2st64_b32 v[42:43], v79 offset0:28 offset1:29
	v_fmac_f32_e32 v80, v41, v41
	v_fmac_f32_e32 v80, v39, v39
	s_waitcnt lgkmcnt(0)
	v_fma_f32 v40, v44, v64, -v42
	v_fma_f32 v38, v45, v64, -v43
	ds_read2st64_b32 v[42:43], v79 offset0:30 offset1:31
	ds_read2st64_b32 v[44:45], v79 offset0:32 offset1:33
	v_fmac_f32_e32 v80, v40, v40
	v_fmac_f32_e32 v80, v38, v38
	s_waitcnt lgkmcnt(1)
	v_fma_f32 v71, v46, v64, -v42
	v_fma_f32 v47, v47, v64, -v43
	s_waitcnt lgkmcnt(0)
	v_fma_f32 v43, v16, v64, -v44
	v_fma_f32 v42, v17, v64, -v45
	ds_read2st64_b32 v[16:17], v79 offset0:34 offset1:35
	v_fmac_f32_e32 v80, v71, v71
	v_fmac_f32_e32 v80, v47, v47
	v_fmac_f32_e32 v80, v43, v43
	v_fmac_f32_e32 v80, v42, v42
	s_waitcnt lgkmcnt(0)
	v_fma_f32 v70, v18, v64, -v16
	v_fma_f32 v45, v19, v64, -v17
	ds_read2st64_b32 v[16:17], v79 offset0:36 offset1:37
	v_fmac_f32_e32 v80, v70, v70
	v_fmac_f32_e32 v80, v45, v45
	s_waitcnt lgkmcnt(0)
	v_fma_f32 v46, v20, v64, -v16
	v_fma_f32 v44, v21, v64, -v17
	ds_read2st64_b32 v[16:17], v79 offset0:38 offset1:39
	v_fmac_f32_e32 v80, v46, v46
	v_fmac_f32_e32 v80, v44, v44
	s_waitcnt lgkmcnt(0)
	v_fma_f32 v77, v22, v64, -v16
	v_fma_f32 v75, v23, v64, -v17
	ds_read2st64_b32 v[16:17], v79 offset0:40 offset1:41
	v_fmac_f32_e32 v80, v77, v77
	v_fmac_f32_e32 v80, v75, v75
	s_waitcnt lgkmcnt(0)
; __device__ __forceinline__ void attn_unit(LAS unsigned char* lds, const bf16_t* Qb, const bf16_t* Kb, const bf16_t* Vb, bf16_t* mix,
;                                           int b, int head, int qbase  , float lam, float post_scale, const float* subg) {
;     ...
;             for (int i = 0; i < 16; ++i) { const float o = O[d][i] * i0 - X[(d * 16 + i) * 64]; O[d][i] = o; ss += o * o; }
;         ss += __shfl_xor(ss, 32);
;         const float rn = rsqrtf(ss * (1.f / 128.f) + EPSN) * post_scale;
;         const int qrow = qbase < CTXL ? (MLAT + b * CTXL + qidx_e) : (b * SEQ + qidx_e - CTXL);
;         bf16_t* orow = mix + (size_t)qrow * DM + head * 128;
	v_fma_f32 v73, v24, v64, -v16
	v_fma_f32 v72, v25, v64, -v17
	ds_read2st64_b32 v[16:17], v79 offset0:42 offset1:43
	v_fmac_f32_e32 v80, v73, v73
	v_fmac_f32_e32 v80, v72, v72
	s_waitcnt lgkmcnt(0)
	v_fma_f32 v76, v26, v64, -v16
	v_fma_f32 v74, v27, v64, -v17
	ds_read2st64_b32 v[16:17], v79 offset0:44 offset1:45
	v_fmac_f32_e32 v80, v76, v76
	v_fmac_f32_e32 v80, v74, v74
	s_waitcnt lgkmcnt(0)
	v_fma_f32 v27, v28, v64, -v16
	v_fma_f32 v26, v29, v64, -v17
	ds_read2st64_b32 v[16:17], v79 offset0:46 offset1:47
	v_fmac_f32_e32 v80, v27, v27
	v_fmac_f32_e32 v80, v26, v26
	s_waitcnt lgkmcnt(0)
	v_fma_f32 v29, v30, v64, -v16
	v_fma_f32 v28, v31, v64, -v17
	ds_read2st64_b32 v[16:17], v79 offset0:48 offset1:49
	v_fmac_f32_e32 v80, v29, v29
	v_fmac_f32_e32 v80, v28, v28
	s_waitcnt lgkmcnt(0)
	v_fma_f32 v25, v0, v64, -v16
	v_fma_f32 v24, v1, v64, -v17
	ds_read2st64_b32 v[0:1], v79 offset0:50 offset1:51
	v_fmac_f32_e32 v80, v25, v25
	v_fmac_f32_e32 v80, v24, v24
	s_waitcnt lgkmcnt(0)
	v_fma_f32 v23, v2, v64, -v0
	v_fma_f32 v22, v3, v64, -v1
	ds_read2st64_b32 v[0:1], v79 offset0:52 offset1:53
	v_fmac_f32_e32 v80, v23, v23
	v_fmac_f32_e32 v80, v22, v22
	s_waitcnt lgkmcnt(0)
	v_fma_f32 v21, v4, v64, -v0
	v_fma_f32 v20, v5, v64, -v1
	ds_read2st64_b32 v[0:1], v79 offset0:54 offset1:55
	v_fmac_f32_e32 v80, v21, v21
	v_fmac_f32_e32 v80, v20, v20
	s_waitcnt lgkmcnt(0)
	v_pk_fma_f32 v[18:19], v[6:7], v[64:65], v[0:1] op_sel_hi:[1,0,1] neg_lo:[0,0,1] neg_hi:[0,0,1]
	s_nop 0
	v_pk_mul_f32 v[0:1], v[18:19], v[18:19]
	s_nop 0
	v_add_f32_e32 v0, v80, v0
	v_add_f32_e32 v2, v0, v1
	ds_read2st64_b32 v[0:1], v79 offset0:56 offset1:57
	s_waitcnt lgkmcnt(0)
	v_pk_fma_f32 v[16:17], v[8:9], v[64:65], v[0:1] op_sel_hi:[1,0,1] neg_lo:[0,0,1] neg_hi:[0,0,1]
	s_nop 0
	v_pk_mul_f32 v[0:1], v[16:17], v[16:17]
	s_nop 0
	v_add_f32_e32 v0, v2, v0
	v_add_f32_e32 v2, v0, v1
	ds_read2st64_b32 v[0:1], v79 offset0:58 offset1:59
	s_waitcnt lgkmcnt(0)
	v_pk_fma_f32 v[8:9], v[10:11], v[64:65], v[0:1] op_sel_hi:[1,0,1] neg_lo:[0,0,1] neg_hi:[0,0,1]
	s_nop 0
	v_pk_mul_f32 v[0:1], v[8:9], v[8:9]
	s_nop 0
	v_add_f32_e32 v0, v2, v0
	v_add_f32_e32 v2, v0, v1
	ds_read2st64_b32 v[0:1], v79 offset0:60 offset1:61
	s_waitcnt lgkmcnt(0)
	v_pk_fma_f32 v[6:7], v[12:13], v[64:65], v[0:1] op_sel_hi:[1,0,1] neg_lo:[0,0,1] neg_hi:[0,0,1]
	s_nop 0
	v_pk_mul_f32 v[0:1], v[6:7], v[6:7]
	s_nop 0
	v_add_f32_e32 v0, v2, v0
	v_add_f32_e32 v2, v0, v1
	ds_read2st64_b32 v[0:1], v79 offset0:62 offset1:63
	s_waitcnt lgkmcnt(0)
	v_pk_fma_f32 v[4:5], v[14:15], v[64:65], v[0:1] op_sel_hi:[1,0,1] neg_lo:[0,0,1] neg_hi:[0,0,1]
	s_nop 0
	v_pk_mul_f32 v[0:1], v[4:5], v[4:5]
	s_nop 0
	v_add_f32_e32 v0, v2, v0
	v_add_f32_e32 v0, v0, v1
	ds_bpermute_b32 v1, v78, v0
	s_waitcnt lgkmcnt(0)
	v_add_f32_e32 v0, v0, v1
	v_fmamk_f32 v0, v0, 0x3c000000, v224
	v_cmp_gt_f32_e32 vcc, s33, v0
	v_mul_f32_e32 v1, 0x4b800000, v0
	s_nop 0
	v_cndmask_b32_e32 v0, v0, v1, vcc
	v_rsq_f32_e32 v0, v0
	s_nop 0
	v_mul_f32_e32 v1, 0x45800000, v0
	v_cndmask_b32_e32 v0, v0, v1, vcc
	v_mul_f32_e32 v12, v169, v0
	v_and_or_b32 v0, v67, 31, s0
	v_ashrrev_i32_e32 v1, 31, v0
	v_lshlrev_b64 v[0:1], 11, v[0:1]
	s_lshl_b32 s0, s41, 8
	v_lshl_add_u64 v[0:1], s[8:9], 0, v[0:1]
	s_and_b32 s76, s0, 0x300
	v_lshl_add_u64 v[10:11], v[0:1], 0, s[76:77]
	v_lshrrev_b32_e32 v0, 3, v67
	v_and_b32_e32 v30, 4, v0
	v_lshlrev_b32_e32 v13, 2, v30
	v_mul_f32_e32 v14, v65, v12
	v_lshlrev_b32_e32 v176, 1, v30
	s_waitcnt vmcnt(0)
; __device__ __forceinline__ unsigned pkbf(float lo, float hi) { return pg8::cvt_pk_bf16(lo, hi); }
; __device__ __forceinline__ void attn_unit(LAS unsigned char* lds, const bf16_t* Qb, const bf16_t* Kb, const bf16_t* Vb, bf16_t* mix,
;                                           int b, int head, int qbase  , float lam, float post_scale, const float* subg) {
;     ...
; #pragma unroll
;         for (int d = 0; d < 4; ++d)
; #pragma unroll
;             for (int i4 = 0; i4 < 4; ++i4) {
;                 const int dv = 32 * d + 8 * i4 + 4 * h_e;
;                 const f32x4 g = *(const f32x4*)(subg + dv);
;                 u32x2 w; w.x = pkbf(O[d][4 * i4] * rn * g[0], O[d][4 * i4 + 1] * rn * g[1]); w.y = pkbf(O[d][4 * i4 + 2] * rn * g[2], O[d][4 * i4 + 3] * rn * g[3]);
;                 *(u32x2*)(orow + dv) = w;
;             }
	v_mul_f32_e32 v0, v84, v14
	v_mul_f32_e32 v14, v48, v12
	v_mul_f32_e32 v1, v85, v14
	v_cvt_pk_bf16_f32 v14, v0, v1
	v_mul_f32_e32 v0, v49, v12
	v_mul_f32_e32 v1, v50, v12
	v_mul_f32_e32 v0, v86, v0
	v_mul_f32_e32 v1, v87, v1
	v_cvt_pk_bf16_f32 v15, v0, v1
	v_lshl_add_u64 v[0:1], v[10:11], 0, v[176:177]
	flat_store_dwordx2 v[0:1], v[14:15]
	v_mul_f32_e32 v2, v51, v12
	v_mul_f32_e32 v3, v52, v12
	v_mul_f32_e32 v10, v54, v12
	v_mul_f32_e32 v2, v88, v2
	v_mul_f32_e32 v3, v89, v3
	v_cvt_pk_bf16_f32 v2, v2, v3
	v_mul_f32_e32 v3, v53, v12
	v_mul_f32_e32 v3, v90, v3
	v_mul_f32_e32 v10, v91, v10
	v_cvt_pk_bf16_f32 v3, v3, v10
	flat_store_dwordx2 v[0:1], v[2:3] offset:16
	v_mul_f32_e32 v2, v56, v12
	v_mul_f32_e32 v3, v55, v12
	v_mul_f32_e32 v10, v58, v12
	v_mul_f32_e32 v2, v92, v2
	v_mul_f32_e32 v3, v93, v3
	v_cvt_pk_bf16_f32 v2, v2, v3
	v_mul_f32_e32 v3, v66, v12
	v_mul_f32_e32 v3, v94, v3
	v_mul_f32_e32 v10, v95, v10
	v_cvt_pk_bf16_f32 v3, v3, v10
	flat_store_dwordx2 v[0:1], v[2:3] offset:32
	v_mul_f32_e32 v2, v59, v12
	v_mul_f32_e32 v3, v57, v12
	v_mul_f32_e32 v10, v61, v12
	v_mul_f32_e32 v2, v2, v96
	v_mul_f32_e32 v3, v3, v97
	v_cvt_pk_bf16_f32 v2, v2, v3
	v_mul_f32_e32 v3, v68, v12
	v_mul_f32_e32 v3, v3, v98
	v_mul_f32_e32 v10, v10, v99
	v_cvt_pk_bf16_f32 v3, v3, v10
	flat_store_dwordx2 v[0:1], v[2:3] offset:48
	v_mul_f32_e32 v2, v60, v12
	v_mul_f32_e32 v3, v32, v12
	v_mul_f32_e32 v10, v34, v12
	v_mul_f32_e32 v2, v2, v100
	v_mul_f32_e32 v3, v3, v101
	v_cvt_pk_bf16_f32 v2, v2, v3
	v_mul_f32_e32 v3, v62, v12
	v_mul_f32_e32 v3, v3, v102
	v_mul_f32_e32 v10, v10, v103
	v_cvt_pk_bf16_f32 v3, v3, v10
	flat_store_dwordx2 v[0:1], v[2:3] offset:64
	v_mul_f32_e32 v2, v35, v12
	v_mul_f32_e32 v3, v33, v12
	v_mul_f32_e32 v10, v63, v12
	v_mul_f32_e32 v2, v2, v104
	v_mul_f32_e32 v3, v3, v105
	v_cvt_pk_bf16_f32 v2, v2, v3
	v_mul_f32_e32 v3, v69, v12
	v_mul_f32_e32 v3, v3, v106
	v_mul_f32_e32 v10, v10, v107
	v_cvt_pk_bf16_f32 v3, v3, v10
	flat_store_dwordx2 v[0:1], v[2:3] offset:80
	v_mul_f32_e32 v2, v37, v12
	v_mul_f32_e32 v3, v36, v12
	v_mul_f32_e32 v10, v39, v12
	v_mul_f32_e32 v2, v2, v108
	v_mul_f32_e32 v3, v3, v109
	v_cvt_pk_bf16_f32 v2, v2, v3
	v_mul_f32_e32 v3, v41, v12
	v_mul_f32_e32 v3, v3, v110
	v_mul_f32_e32 v10, v10, v111
	v_cvt_pk_bf16_f32 v3, v3, v10
	flat_store_dwordx2 v[0:1], v[2:3] offset:96
	v_mul_f32_e32 v2, v40, v12
	v_mul_f32_e32 v3, v38, v12
	v_mul_f32_e32 v10, v47, v12
	v_mul_f32_e32 v2, v2, v112
	v_mul_f32_e32 v3, v3, v113
	v_cvt_pk_bf16_f32 v2, v2, v3
	v_mul_f32_e32 v3, v71, v12
	v_mul_f32_e32 v3, v3, v114
	v_mul_f32_e32 v10, v10, v115
	v_cvt_pk_bf16_f32 v3, v3, v10
	flat_store_dwordx2 v[0:1], v[2:3] offset:112
	v_mul_f32_e32 v2, v43, v12
	v_mul_f32_e32 v3, v42, v12
	v_mul_f32_e32 v10, v45, v12
	v_mul_f32_e32 v2, v2, v116
	v_mul_f32_e32 v3, v3, v117
	v_cvt_pk_bf16_f32 v2, v2, v3
	v_mul_f32_e32 v3, v70, v12
	v_mul_f32_e32 v3, v3, v118
	v_mul_f32_e32 v10, v10, v119
	v_cvt_pk_bf16_f32 v3, v3, v10
	flat_store_dwordx2 v[0:1], v[2:3] offset:128
	v_mul_f32_e32 v2, v46, v12
	v_mul_f32_e32 v3, v44, v12
	v_mul_f32_e32 v10, v75, v12
	v_mul_f32_e32 v2, v2, v120
	v_mul_f32_e32 v3, v3, v121
	v_cvt_pk_bf16_f32 v2, v2, v3
	v_mul_f32_e32 v3, v77, v12
	v_mul_f32_e32 v3, v3, v122
	v_mul_f32_e32 v10, v10, v123
	v_cvt_pk_bf16_f32 v3, v3, v10
	flat_store_dwordx2 v[0:1], v[2:3] offset:144
	v_mul_f32_e32 v2, v73, v12
	v_mul_f32_e32 v3, v72, v12
	v_mul_f32_e32 v10, v74, v12
	v_mul_f32_e32 v2, v2, v124
	v_mul_f32_e32 v3, v3, v125
	v_cvt_pk_bf16_f32 v2, v2, v3
	v_mul_f32_e32 v3, v76, v12
	v_mul_f32_e32 v3, v3, v126
	v_mul_f32_e32 v10, v10, v127
	v_cvt_pk_bf16_f32 v3, v3, v10
	flat_store_dwordx2 v[0:1], v[2:3] offset:160
	v_mul_f32_e32 v2, v27, v12
	v_mul_f32_e32 v3, v26, v12
	v_mul_f32_e32 v10, v28, v12
	v_mul_f32_e32 v2, v2, v128
	v_mul_f32_e32 v3, v3, v129
	v_cvt_pk_bf16_f32 v2, v2, v3
	v_mul_f32_e32 v3, v29, v12
	v_mul_f32_e32 v3, v3, v130
	v_mul_f32_e32 v10, v10, v131
	v_cvt_pk_bf16_f32 v3, v3, v10
	flat_store_dwordx2 v[0:1], v[2:3] offset:176
	v_mul_f32_e32 v2, v25, v12
	v_mul_f32_e32 v3, v24, v12
	v_mul_f32_e32 v10, v22, v12
	v_mul_f32_e32 v2, v2, v132
	v_mul_f32_e32 v3, v3, v133
	v_cvt_pk_bf16_f32 v2, v2, v3
	v_mul_f32_e32 v3, v23, v12
	v_mul_f32_e32 v3, v3, v134
	v_mul_f32_e32 v10, v10, v135
	v_cvt_pk_bf16_f32 v3, v3, v10
	flat_store_dwordx2 v[0:1], v[2:3] offset:192
	v_mul_f32_e32 v2, v21, v12
	v_mul_f32_e32 v3, v20, v12
	v_mul_f32_e32 v10, v19, v12
	v_mul_f32_e32 v2, v2, v136
	v_mul_f32_e32 v3, v3, v137
	v_cvt_pk_bf16_f32 v2, v2, v3
	v_mul_f32_e32 v3, v18, v12
	v_mul_f32_e32 v3, v3, v138
	v_mul_f32_e32 v10, v10, v139
	v_cvt_pk_bf16_f32 v3, v3, v10
	flat_store_dwordx2 v[0:1], v[2:3] offset:208
	v_mul_f32_e32 v2, v16, v12
	v_mul_f32_e32 v3, v17, v12
	v_mul_f32_e32 v2, v2, v140
	v_mul_f32_e32 v3, v3, v141
	v_cvt_pk_bf16_f32 v2, v2, v3
	v_mul_f32_e32 v3, v8, v12
	v_mul_f32_e32 v3, v3, v142
	v_mul_f32_e32 v8, v9, v12
	v_mul_f32_e32 v8, v8, v143
	v_cvt_pk_bf16_f32 v3, v3, v8
	flat_store_dwordx2 v[0:1], v[2:3] offset:224
	v_mul_f32_e32 v2, v6, v12
	v_mul_f32_e32 v3, v7, v12
	v_mul_f32_e32 v2, v2, v144
	v_mul_f32_e32 v3, v3, v145
	v_cvt_pk_bf16_f32 v2, v2, v3
	v_mul_f32_e32 v3, v4, v12
	v_mul_f32_e32 v3, v3, v146
	v_mul_f32_e32 v4, v5, v12
	v_mul_f32_e32 v4, v4, v147
	v_cvt_pk_bf16_f32 v3, v3, v4
	flat_store_dwordx2 v[0:1], v[2:3] offset:240
	s_branch .LBB0_337
